# v9 plus L1-bypass (sc1) on the attention loop K/V LDS-DMA loads
# speedup vs baseline: 1.0054x; 1.0054x over previous
; #define LAS __attribute__((address_space(3)))
; __device__ __forceinline__ int pi32(int i) { return (i & 0x13) | ((i & 4) << 1) | ((i & 8) >> 1); }
; #define ATT_WAITBAR(N) asm volatile("s_waitcnt vmcnt(" #N ") lgkmcnt(0)\n\ts_barrier" ::: "memory")
; #define ATT_PV(slot) do { bf16x8 va[4], vb[4]; ATT_LDV(va, slot, 0); ATT_SB; ATT_LDV(vb, slot, 1); ATT_SB; ATT_MMV(va, 0); ATT_SB; ATT_LDV(va, slot, 2); ATT_SB; ATT_MMV(vb, 1); ATT_SB; \
;         ATT_LDV(vb, slot, 3); ATT_SB; ATT_MMV(va, 2); ATT_SB; ATT_MMV(vb, 3); ATT_SB; } while (0)
; template <bool NOSHIFT> __device__ __forceinline__ void diff_attn_unit(LAS unsigned char* lds, bf16_t* proj, const bf16_t* VT, int b, int h, int qb, const AttnConsts ac, const float* gsub, const int tid, bf16_t* obuf, int opitch, int ocol) {
;     ...
;     const int krow = pi32(i32);
;     int koff[2][4];
; #pragma unroll
;     for (int mt = 0; mt < 2; ++mt)
; #pragma unroll
;         for (int ks = 0; ks < 4; ++ks) { const int r = 32 * mt + krow; koff[mt][ks] = r * 256 + (((8 * c + 2 * ks + hi) ^ (r & 15)) * 16); }
;     const int NT = 2 * qb + 2;
;     f32x16 o[4];
; #pragma unroll
;     for (int dt = 0; dt < 4; ++dt)
; #pragma unroll
;         for (int r = 0; r < 16; ++r) o[dt][r] = 0.f;
;     float l = 0.f;
;     bf16x8 pf[4];
; #pragma unroll
;     for (int kk = 0; kk < 4; ++kk) pf[kk] = (bf16x8){0, 0, 0, 0, 0, 0, 0, 0};
;     const int qmax = q0 + 32 * wq + 31;
;     ...
;     ATT_ISSUE(0); ATT_ISSUE(1);
;     ATT_WAITBAR(4);
;     for (int t = 0; t < NT; ++t) {
;         const int bo = (t & 3) * 16384, sl_cur = bo, sl_prev = ((t - 1) & 3) * 16384;
;         if (t + 2 < NT) ATT_ISSUE(t + 2);
;         const int kv0 = 64 * t;
;         if (c == 1 && t >= 1 && kv0 - 64 <= qmax) ATT_PV(sl_prev);
;         if (kv0 <= qmax) {
;             f32x16 p[2];
;             bf16x8 kf[2][4];
; #pragma unroll
;             for (int mt = 0; mt < 2; ++mt)
; #pragma unroll
;                 for (int ks = 0; ks < 4; ++ks) kf[mt][ks] = *(const LAS bf16x8*)(lds + bo + koff[mt][ks]);
.LBB1_290:
	s_addk_i32 s14, 0x4000
	s_cmp_gt_u32 s47, s44
	s_cbranch_scc1 .LBB1_297
	s_and_b32 s15, s14, 0xc000
	s_add_i32 s80, s15, 0
	v_add_u32_e32 v7, s80, v179
	v_add_u32_e32 v96, s80, v183
	v_add_u32_e32 v97, s80, v186
	v_add_u32_e32 v98, s80, v187
	ds_read_b128 v[8:11], v7
	ds_read_b128 v[12:15], v7 offset:8192
	ds_read_b128 v[128:131], v96
	ds_read_b128 v[132:135], v96 offset:8192
	ds_read_b128 v[136:139], v97
	ds_read_b128 v[140:143], v97 offset:8192
	ds_read_b128 v[144:147], v98
	ds_read_b128 v[148:151], v98 offset:8192
	s_and_b64 vcc, exec, s[78:79]
	s_cbranch_vccnz .Latt_nodma
	s_add_i32 s80, s14, 0x8000
	v_lshl_add_u64 v[152:153], s[96:97], 0, v[4:5]
	s_mov_b64 s[16:17], 0x9e82000
	s_and_b32 s80, s80, 0xc000
	v_lshl_add_u64 v[154:155], v[152:153], 0, s[16:17]
	s_add_i32 s81, s80, s59
	s_mov_b32 m0, s81
	v_lshl_add_u64 v[156:157], s[96:97], 0, v[2:3]
	global_load_lds_dwordx4 v[154:155], off sc1
	s_mov_b64 s[16:17], 0x9f42000
	s_addk_i32 s81, 0x2000
	v_lshl_add_u64 v[152:153], v[152:153], 0, s[16:17]
	s_mov_b32 m0, s81
	s_mov_b64 s[16:17], 0x21a00180
	global_load_lds_dwordx4 v[152:153], off sc1
	v_lshl_add_u64 v[158:159], v[156:157], 0, s[16:17]
	s_add_i32 s81, s80, s54
	s_mov_b32 m0, s81
	s_mov_b64 s[16:17], 0x21c00180
	global_load_lds_dwordx4 v[158:159], off sc1
	v_lshl_add_u64 v[156:157], v[156:157], 0, s[16:17]
	s_addk_i32 s81, 0x2000
	s_mov_b32 m0, s81
	s_nop 0
	global_load_lds_dwordx4 v[156:157], off sc1
